# GEMM K-loops: m0-write -> LDS-DMA hazard slot filled with the DMA's own address add (s_nop 0 removed), 8 sites per loop
# baseline (speedup 1.0000x reference)
.LBB0_149:
	ds_read_b128 v[128:131], v164
	ds_read_b128 v[150:153], v164 offset:1024
	ds_read_b128 v[154:157], v164 offset:2048
	ds_read_b128 v[158:161], v164 offset:3072
	ds_read_b128 v[170:173], v165
	ds_read_b128 v[174:177], v165 offset:1024
	ds_read_b128 v[178:181], v165 offset:2048
	ds_read_b128 v[182:185], v165 offset:3072
	s_add_u32 s17, s42, 0xfff80080
	s_addc_u32 s19, s43, -1
	s_cmp_eq_u32 s16, 28
	s_cselect_b32 s77, s0, s19
	s_cselect_b32 s76, s1, s17
	s_cselect_b32 s75, s12, s15
	s_cselect_b32 s74, s13, s14
	v_lshl_add_u64 v[218:219], s[42:43], 0, v[142:143]
	s_add_i32 m0, s84, 0xc000
	ds_read_b128 v[186:189], v166
	ds_read_b128 v[190:193], v166 offset:1024
	ds_read_b128 v[194:197], v166 offset:2048
	ds_read_b128 v[198:201], v166 offset:3072
	ds_read_b128 v[202:205], v166 offset:4096
	ds_read_b128 v[206:209], v166 offset:5120
	ds_read_b128 v[210:213], v166 offset:6144
	ds_read_b128 v[214:217], v166 offset:7168
	global_load_lds_dwordx4 v[218:219], off
	s_add_i32 m0, s84, 0xe000
	v_lshl_add_u64 v[218:219], s[42:43], 0, v[144:145]
	global_load_lds_dwordx4 v[218:219], off
	s_waitcnt vmcnt(8)
	s_waitcnt lgkmcnt(0)
	s_barrier
	s_setprio 1
	s_waitcnt lgkmcnt(0)
	v_mfma_f32_16x16x32_bf16 v[124:127], v[128:131], v[186:189], v[124:127]
	v_mfma_f32_16x16x32_bf16 v[120:123], v[154:157], v[186:189], v[120:123]
	v_mfma_f32_16x16x32_bf16 v[108:111], v[128:131], v[194:197], v[108:111]
	v_mfma_f32_16x16x32_bf16 v[104:107], v[154:157], v[194:197], v[104:107]
	v_mfma_f32_16x16x32_bf16 v[92:95], v[128:131], v[202:205], v[92:95]
	v_mfma_f32_16x16x32_bf16 v[88:91], v[154:157], v[202:205], v[88:91]
	v_mfma_f32_16x16x32_bf16 v[76:79], v[128:131], v[210:213], v[76:79]
	v_mfma_f32_16x16x32_bf16 v[72:75], v[154:157], v[210:213], v[72:75]
	v_mfma_f32_16x16x32_bf16 v[124:127], v[150:153], v[190:193], v[124:127]
	v_mfma_f32_16x16x32_bf16 v[120:123], v[158:161], v[190:193], v[120:123]
	v_mfma_f32_16x16x32_bf16 v[108:111], v[150:153], v[198:201], v[108:111]
	v_mfma_f32_16x16x32_bf16 v[104:107], v[158:161], v[198:201], v[104:107]
	v_mfma_f32_16x16x32_bf16 v[92:95], v[150:153], v[206:209], v[92:95]
	v_mfma_f32_16x16x32_bf16 v[88:91], v[158:161], v[206:209], v[88:91]
	v_mfma_f32_16x16x32_bf16 v[76:79], v[150:153], v[214:217], v[76:79]
	v_mfma_f32_16x16x32_bf16 v[72:75], v[158:161], v[214:217], v[72:75]
	s_setprio 0
	s_setprio 1
	v_mfma_f32_16x16x32_bf16 v[116:119], v[170:173], v[186:189], v[116:119]
	v_mfma_f32_16x16x32_bf16 v[112:115], v[178:181], v[186:189], v[112:115]
	v_mfma_f32_16x16x32_bf16 v[100:103], v[170:173], v[194:197], v[100:103]
	v_mfma_f32_16x16x32_bf16 v[96:99], v[178:181], v[194:197], v[96:99]
	v_mfma_f32_16x16x32_bf16 v[84:87], v[170:173], v[202:205], v[84:87]
	v_mfma_f32_16x16x32_bf16 v[80:83], v[178:181], v[202:205], v[80:83]
	v_mfma_f32_16x16x32_bf16 v[68:71], v[170:173], v[210:213], v[68:71]
	v_mfma_f32_16x16x32_bf16 v[64:67], v[178:181], v[210:213], v[64:67]
	v_mfma_f32_16x16x32_bf16 v[116:119], v[174:177], v[190:193], v[116:119]
	v_mfma_f32_16x16x32_bf16 v[112:115], v[182:185], v[190:193], v[112:115]
	v_mfma_f32_16x16x32_bf16 v[100:103], v[174:177], v[198:201], v[100:103]
	v_mfma_f32_16x16x32_bf16 v[96:99], v[182:185], v[198:201], v[96:99]
	v_mfma_f32_16x16x32_bf16 v[84:87], v[174:177], v[206:209], v[84:87]
	v_mfma_f32_16x16x32_bf16 v[80:83], v[182:185], v[206:209], v[80:83]
	v_mfma_f32_16x16x32_bf16 v[68:71], v[174:177], v[214:217], v[68:71]
	v_mfma_f32_16x16x32_bf16 v[64:67], v[182:185], v[214:217], v[64:67]
	s_setprio 0
	s_barrier
	s_add_i32 s17, s93, s83
	v_lshl_add_u64 v[218:219], s[74:75], 0, v[134:135]
	s_mov_b32 m0, s17
	ds_read_b128 v[186:189], v166 offset:16384
	ds_read_b128 v[190:193], v166 offset:17408
	ds_read_b128 v[194:197], v166 offset:18432
	ds_read_b128 v[198:201], v166 offset:19456
	ds_read_b128 v[202:205], v166 offset:20480
	ds_read_b128 v[206:209], v166 offset:21504
	ds_read_b128 v[210:213], v166 offset:22528
	ds_read_b128 v[214:217], v166 offset:23552
	global_load_lds_dwordx4 v[218:219], off
	s_add_i32 m0, s17, 0x2000
	s_add_u32 s20, s74, 0x80000
	v_lshl_add_u64 v[220:221], s[74:75], 0, v[138:139]
	s_addc_u32 s21, s75, 0
	s_add_i32 s17, s94, s83
	global_load_lds_dwordx4 v[220:221], off
	v_lshl_add_u64 v[222:223], s[20:21], 0, v[134:135]
	s_mov_b32 m0, s17
	v_lshl_add_u64 v[224:225], s[76:77], 0, v[136:137]
	global_load_lds_dwordx4 v[222:223], off
	s_add_i32 m0, s17, 0x2000
	v_lshl_add_u64 v[222:223], s[20:21], 0, v[138:139]
	global_load_lds_dwordx4 v[222:223], off
	s_mov_b32 m0, s84
	v_lshl_add_u64 v[222:223], s[76:77], 0, v[132:133]
	global_load_lds_dwordx4 v[222:223], off
	s_mov_b32 m0, s85
	s_nop 0
	global_load_lds_dwordx4 v[224:225], off
	s_waitcnt vmcnt(8)
	s_waitcnt lgkmcnt(0)
	s_barrier
	s_setprio 1
	s_waitcnt lgkmcnt(0)
	v_mfma_f32_16x16x32_bf16 v[60:63], v[128:131], v[186:189], v[60:63]
	v_mfma_f32_16x16x32_bf16 v[56:59], v[154:157], v[186:189], v[56:59]
	v_mfma_f32_16x16x32_bf16 v[44:47], v[128:131], v[194:197], v[44:47]
	v_mfma_f32_16x16x32_bf16 v[40:43], v[154:157], v[194:197], v[40:43]
	v_mfma_f32_16x16x32_bf16 v[28:31], v[128:131], v[202:205], v[28:31]
	v_mfma_f32_16x16x32_bf16 v[24:27], v[154:157], v[202:205], v[24:27]
	v_mfma_f32_16x16x32_bf16 v[12:15], v[128:131], v[210:213], v[12:15]
	v_mfma_f32_16x16x32_bf16 v[8:11], v[154:157], v[210:213], v[8:11]
	v_mfma_f32_16x16x32_bf16 v[60:63], v[150:153], v[190:193], v[60:63]
	v_mfma_f32_16x16x32_bf16 v[56:59], v[158:161], v[190:193], v[56:59]
	v_mfma_f32_16x16x32_bf16 v[44:47], v[150:153], v[198:201], v[44:47]
	v_mfma_f32_16x16x32_bf16 v[40:43], v[158:161], v[198:201], v[40:43]
	v_mfma_f32_16x16x32_bf16 v[28:31], v[150:153], v[206:209], v[28:31]
	v_mfma_f32_16x16x32_bf16 v[24:27], v[158:161], v[206:209], v[24:27]
	v_mfma_f32_16x16x32_bf16 v[12:15], v[150:153], v[214:217], v[12:15]
	v_mfma_f32_16x16x32_bf16 v[8:11], v[158:161], v[214:217], v[8:11]
	s_setprio 0
	s_setprio 1
	v_mfma_f32_16x16x32_bf16 v[52:55], v[170:173], v[186:189], v[52:55]
	v_mfma_f32_16x16x32_bf16 v[48:51], v[178:181], v[186:189], v[48:51]
	v_mfma_f32_16x16x32_bf16 v[36:39], v[170:173], v[194:197], v[36:39]
	v_mfma_f32_16x16x32_bf16 v[32:35], v[178:181], v[194:197], v[32:35]
	v_mfma_f32_16x16x32_bf16 v[20:23], v[170:173], v[202:205], v[20:23]
	v_mfma_f32_16x16x32_bf16 v[16:19], v[178:181], v[202:205], v[16:19]
	v_mfma_f32_16x16x32_bf16 v[4:7], v[170:173], v[210:213], v[4:7]
	v_mfma_f32_16x16x32_bf16 v[0:3], v[178:181], v[210:213], v[0:3]
	v_mfma_f32_16x16x32_bf16 v[52:55], v[174:177], v[190:193], v[52:55]
	v_mfma_f32_16x16x32_bf16 v[48:51], v[182:185], v[190:193], v[48:51]
	v_mfma_f32_16x16x32_bf16 v[36:39], v[174:177], v[198:201], v[36:39]
	v_mfma_f32_16x16x32_bf16 v[32:35], v[182:185], v[198:201], v[32:35]
	v_mfma_f32_16x16x32_bf16 v[20:23], v[174:177], v[206:209], v[20:23]
	v_mfma_f32_16x16x32_bf16 v[16:19], v[182:185], v[206:209], v[16:19]
	v_mfma_f32_16x16x32_bf16 v[4:7], v[174:177], v[214:217], v[4:7]
	v_mfma_f32_16x16x32_bf16 v[0:3], v[182:185], v[214:217], v[0:3]
	s_setprio 0
	s_barrier
	s_add_i32 s17, 0, 0x18000
	v_add_u32_e32 v140, s17, v162
	s_add_i32 s19, 0, 0x1c000
	ds_read_b128 v[128:131], v140
	ds_read_b128 v[150:153], v140 offset:1024
	ds_read_b128 v[154:157], v140 offset:2048
	ds_read_b128 v[158:161], v140 offset:3072
	v_add_u32_e32 v140, s19, v162
	ds_read_b128 v[170:173], v140
	ds_read_b128 v[174:177], v140 offset:1024
	ds_read_b128 v[178:181], v140 offset:2048
	ds_read_b128 v[182:185], v140 offset:3072
	s_add_u32 s20, s76, 0x80000
	s_addc_u32 s21, s77, 0
	s_mov_b32 m0, s86
	v_lshl_add_u64 v[226:227], s[20:21], 0, v[132:133]
	ds_read_b128 v[186:189], v166 offset:32768
	ds_read_b128 v[190:193], v166 offset:33792
	ds_read_b128 v[194:197], v166 offset:34816
	ds_read_b128 v[198:201], v166 offset:35840
	ds_read_b128 v[202:205], v166 offset:36864
	ds_read_b128 v[206:209], v166 offset:37888
	ds_read_b128 v[210:213], v166 offset:38912
	ds_read_b128 v[214:217], v166 offset:39936
	global_load_lds_dwordx4 v[226:227], off
	s_mov_b32 m0, s87
	v_lshl_add_u64 v[226:227], s[20:21], 0, v[136:137]
	global_load_lds_dwordx4 v[226:227], off
	s_waitcnt vmcnt(8)
	s_waitcnt lgkmcnt(0)
	s_barrier
	s_setprio 1
	s_waitcnt lgkmcnt(0)
	v_mfma_f32_16x16x32_bf16 v[124:127], v[128:131], v[186:189], v[124:127]
	v_mfma_f32_16x16x32_bf16 v[120:123], v[154:157], v[186:189], v[120:123]
	v_mfma_f32_16x16x32_bf16 v[108:111], v[128:131], v[194:197], v[108:111]
	v_mfma_f32_16x16x32_bf16 v[104:107], v[154:157], v[194:197], v[104:107]
	v_mfma_f32_16x16x32_bf16 v[92:95], v[128:131], v[202:205], v[92:95]
	v_mfma_f32_16x16x32_bf16 v[88:91], v[154:157], v[202:205], v[88:91]
	v_mfma_f32_16x16x32_bf16 v[76:79], v[128:131], v[210:213], v[76:79]
	v_mfma_f32_16x16x32_bf16 v[72:75], v[154:157], v[210:213], v[72:75]
	v_mfma_f32_16x16x32_bf16 v[124:127], v[150:153], v[190:193], v[124:127]
	v_mfma_f32_16x16x32_bf16 v[120:123], v[158:161], v[190:193], v[120:123]
	v_mfma_f32_16x16x32_bf16 v[108:111], v[150:153], v[198:201], v[108:111]
	v_mfma_f32_16x16x32_bf16 v[104:107], v[158:161], v[198:201], v[104:107]
	v_mfma_f32_16x16x32_bf16 v[92:95], v[150:153], v[206:209], v[92:95]
	v_mfma_f32_16x16x32_bf16 v[88:91], v[158:161], v[206:209], v[88:91]
	v_mfma_f32_16x16x32_bf16 v[76:79], v[150:153], v[214:217], v[76:79]
	v_mfma_f32_16x16x32_bf16 v[72:75], v[158:161], v[214:217], v[72:75]
	s_setprio 0
	s_setprio 1
	v_mfma_f32_16x16x32_bf16 v[116:119], v[170:173], v[186:189], v[116:119]
	v_mfma_f32_16x16x32_bf16 v[112:115], v[178:181], v[186:189], v[112:115]
	v_mfma_f32_16x16x32_bf16 v[100:103], v[170:173], v[194:197], v[100:103]
	v_mfma_f32_16x16x32_bf16 v[96:99], v[178:181], v[194:197], v[96:99]
	v_mfma_f32_16x16x32_bf16 v[84:87], v[170:173], v[202:205], v[84:87]
	v_mfma_f32_16x16x32_bf16 v[80:83], v[178:181], v[202:205], v[80:83]
	v_mfma_f32_16x16x32_bf16 v[68:71], v[170:173], v[210:213], v[68:71]
	v_mfma_f32_16x16x32_bf16 v[64:67], v[178:181], v[210:213], v[64:67]
	v_mfma_f32_16x16x32_bf16 v[116:119], v[174:177], v[190:193], v[116:119]
	v_mfma_f32_16x16x32_bf16 v[112:115], v[182:185], v[190:193], v[112:115]
	v_mfma_f32_16x16x32_bf16 v[100:103], v[174:177], v[198:201], v[100:103]
	v_mfma_f32_16x16x32_bf16 v[96:99], v[182:185], v[198:201], v[96:99]
	v_mfma_f32_16x16x32_bf16 v[84:87], v[174:177], v[206:209], v[84:87]
	v_mfma_f32_16x16x32_bf16 v[80:83], v[182:185], v[206:209], v[80:83]
	v_mfma_f32_16x16x32_bf16 v[68:71], v[174:177], v[214:217], v[68:71]
	v_mfma_f32_16x16x32_bf16 v[64:67], v[182:185], v[214:217], v[64:67]
	s_setprio 0
	s_barrier
	s_add_i32 s17, s17, s83
	v_lshl_add_u64 v[218:219], v[218:219], 0, s[10:11]
	s_mov_b32 m0, s17
	ds_read_b128 v[186:189], v166 offset:49152
	ds_read_b128 v[190:193], v166 offset:50176
	ds_read_b128 v[194:197], v166 offset:51200
	ds_read_b128 v[198:201], v166 offset:52224
	ds_read_b128 v[202:205], v166 offset:53248
	ds_read_b128 v[206:209], v166 offset:54272
	ds_read_b128 v[210:213], v166 offset:55296
	ds_read_b128 v[214:217], v166 offset:56320
	global_load_lds_dwordx4 v[218:219], off
	s_add_i32 m0, s17, 0x2000
	s_add_u32 s20, s74, 0x80080
	v_lshl_add_u64 v[218:219], v[220:221], 0, s[10:11]
	s_addc_u32 s21, s75, 0
	s_add_i32 s17, s19, s83
	global_load_lds_dwordx4 v[218:219], off
	s_mov_b32 m0, s17
	v_lshl_add_u64 v[218:219], s[20:21], 0, v[134:135]
	global_load_lds_dwordx4 v[218:219], off
	s_add_i32 m0, s17, 0x2000
	v_lshl_add_u64 v[218:219], s[20:21], 0, v[138:139]
	global_load_lds_dwordx4 v[218:219], off
	s_mov_b32 m0, s91
	v_lshl_add_u64 v[218:219], v[222:223], 0, s[10:11]
	global_load_lds_dwordx4 v[218:219], off
	s_mov_b32 m0, s92
	v_lshl_add_u64 v[218:219], v[224:225], 0, s[10:11]
	global_load_lds_dwordx4 v[218:219], off
	s_waitcnt vmcnt(8)
	s_waitcnt lgkmcnt(0)
	s_barrier
	s_setprio 1
	s_waitcnt lgkmcnt(0)
	v_mfma_f32_16x16x32_bf16 v[60:63], v[128:131], v[186:189], v[60:63]
	v_mfma_f32_16x16x32_bf16 v[56:59], v[154:157], v[186:189], v[56:59]
	v_mfma_f32_16x16x32_bf16 v[44:47], v[128:131], v[194:197], v[44:47]
	v_mfma_f32_16x16x32_bf16 v[40:43], v[154:157], v[194:197], v[40:43]
	v_mfma_f32_16x16x32_bf16 v[28:31], v[128:131], v[202:205], v[28:31]
	v_mfma_f32_16x16x32_bf16 v[24:27], v[154:157], v[202:205], v[24:27]
	v_mfma_f32_16x16x32_bf16 v[12:15], v[128:131], v[210:213], v[12:15]
	v_mfma_f32_16x16x32_bf16 v[8:11], v[154:157], v[210:213], v[8:11]
	v_mfma_f32_16x16x32_bf16 v[60:63], v[150:153], v[190:193], v[60:63]
	v_mfma_f32_16x16x32_bf16 v[56:59], v[158:161], v[190:193], v[56:59]
	v_mfma_f32_16x16x32_bf16 v[44:47], v[150:153], v[198:201], v[44:47]
	v_mfma_f32_16x16x32_bf16 v[40:43], v[158:161], v[198:201], v[40:43]
	v_mfma_f32_16x16x32_bf16 v[28:31], v[150:153], v[206:209], v[28:31]
	v_mfma_f32_16x16x32_bf16 v[24:27], v[158:161], v[206:209], v[24:27]
	v_mfma_f32_16x16x32_bf16 v[12:15], v[150:153], v[214:217], v[12:15]
	v_mfma_f32_16x16x32_bf16 v[8:11], v[158:161], v[214:217], v[8:11]
	s_setprio 0
	s_setprio 1
	v_mfma_f32_16x16x32_bf16 v[52:55], v[170:173], v[186:189], v[52:55]
	v_mfma_f32_16x16x32_bf16 v[48:51], v[178:181], v[186:189], v[48:51]
	v_mfma_f32_16x16x32_bf16 v[36:39], v[170:173], v[194:197], v[36:39]
	v_mfma_f32_16x16x32_bf16 v[32:35], v[178:181], v[194:197], v[32:35]
	v_mfma_f32_16x16x32_bf16 v[20:23], v[170:173], v[202:205], v[20:23]
	v_mfma_f32_16x16x32_bf16 v[16:19], v[178:181], v[202:205], v[16:19]
	v_mfma_f32_16x16x32_bf16 v[4:7], v[170:173], v[210:213], v[4:7]
	v_mfma_f32_16x16x32_bf16 v[0:3], v[178:181], v[210:213], v[0:3]
	v_mfma_f32_16x16x32_bf16 v[52:55], v[174:177], v[190:193], v[52:55]
	v_mfma_f32_16x16x32_bf16 v[48:51], v[182:185], v[190:193], v[48:51]
	v_mfma_f32_16x16x32_bf16 v[36:39], v[174:177], v[198:201], v[36:39]
	v_mfma_f32_16x16x32_bf16 v[32:35], v[182:185], v[198:201], v[32:35]
	v_mfma_f32_16x16x32_bf16 v[20:23], v[174:177], v[206:209], v[20:23]
	v_mfma_f32_16x16x32_bf16 v[16:19], v[182:185], v[206:209], v[16:19]
	v_mfma_f32_16x16x32_bf16 v[4:7], v[174:177], v[214:217], v[4:7]
	v_mfma_f32_16x16x32_bf16 v[0:3], v[182:185], v[214:217], v[0:3]
	s_setprio 0
	s_barrier
	s_add_i32 s16, s16, 2
	s_add_u32 s42, s42, 0x100
	s_addc_u32 s43, s43, 0
	s_add_u32 s14, s14, 0x100
	s_addc_u32 s15, s15, 0
	s_cmp_gt_u32 s16, 29
	s_cbranch_scc0 .LBB0_149
	s_and_b64 vcc, exec, s[30:31]
	s_cbranch_vccz .LBB0_152
	s_barrier

.LBB0_661:
	v_add_u32_e32 v149, s42, v147
	ds_read_b128 v[150:153], v149
	ds_read_b128 v[154:157], v149 offset:1024
	ds_read_b128 v[158:161], v149 offset:2048
	ds_read_b128 v[162:165], v149 offset:3072
	v_add_u32_e32 v149, s43, v147
	s_add_u32 s24, s10, s22
	ds_read_b128 v[170:173], v149
	ds_read_b128 v[174:177], v149 offset:1024
	ds_read_b128 v[178:181], v149 offset:2048
	ds_read_b128 v[182:185], v149 offset:3072
	s_addc_u32 s25, s11, s23
	s_add_u32 s24, s24, 0x100
	s_addc_u32 s25, s25, 0
	s_add_u32 s52, s47, s22
	s_addc_u32 s53, s48, s23
	s_cmpk_eq_i32 s22, 0xf00
	s_cselect_b32 s27, s17, s25
	s_cselect_b32 s26, s49, s24
	s_cselect_b32 s25, s15, s53
	s_cselect_b32 s24, s50, s52
	v_lshl_add_u64 v[166:167], v[140:141], 0, s[22:23]
	s_add_i32 m0, s29, 0xc000
	ds_read_b128 v[186:189], v148
	ds_read_b128 v[190:193], v148 offset:1024
	ds_read_b128 v[194:197], v148 offset:2048
	ds_read_b128 v[198:201], v148 offset:3072
	ds_read_b128 v[202:205], v148 offset:4096
	ds_read_b128 v[206:209], v148 offset:5120
	ds_read_b128 v[210:213], v148 offset:6144
	ds_read_b128 v[214:217], v148 offset:7168
	global_load_lds_dwordx4 v[166:167], off
	s_add_i32 m0, s29, 0xe000
	v_lshl_add_u64 v[166:167], v[142:143], 0, s[22:23]
	global_load_lds_dwordx4 v[166:167], off
	s_waitcnt vmcnt(8)
	s_waitcnt lgkmcnt(0)
	s_barrier
	s_setprio 1
	s_waitcnt lgkmcnt(0)
	v_mfma_f32_16x16x32_bf16 v[124:127], v[150:153], v[186:189], v[124:127]
	v_mfma_f32_16x16x32_bf16 v[120:123], v[158:161], v[186:189], v[120:123]
	v_mfma_f32_16x16x32_bf16 v[108:111], v[150:153], v[194:197], v[108:111]
	v_mfma_f32_16x16x32_bf16 v[104:107], v[158:161], v[194:197], v[104:107]
	v_mfma_f32_16x16x32_bf16 v[92:95], v[150:153], v[202:205], v[92:95]
	v_mfma_f32_16x16x32_bf16 v[88:91], v[158:161], v[202:205], v[88:91]
	v_mfma_f32_16x16x32_bf16 v[76:79], v[150:153], v[210:213], v[76:79]
	v_mfma_f32_16x16x32_bf16 v[72:75], v[158:161], v[210:213], v[72:75]
	v_mfma_f32_16x16x32_bf16 v[124:127], v[154:157], v[190:193], v[124:127]
	v_mfma_f32_16x16x32_bf16 v[120:123], v[162:165], v[190:193], v[120:123]
	v_mfma_f32_16x16x32_bf16 v[108:111], v[154:157], v[198:201], v[108:111]
	v_mfma_f32_16x16x32_bf16 v[104:107], v[162:165], v[198:201], v[104:107]
	v_mfma_f32_16x16x32_bf16 v[92:95], v[154:157], v[206:209], v[92:95]
	v_mfma_f32_16x16x32_bf16 v[88:91], v[162:165], v[206:209], v[88:91]
	v_mfma_f32_16x16x32_bf16 v[76:79], v[154:157], v[214:217], v[76:79]
	v_mfma_f32_16x16x32_bf16 v[72:75], v[162:165], v[214:217], v[72:75]
	s_setprio 0
	s_setprio 1
	v_mfma_f32_16x16x32_bf16 v[116:119], v[170:173], v[186:189], v[116:119]
	v_mfma_f32_16x16x32_bf16 v[112:115], v[178:181], v[186:189], v[112:115]
	v_mfma_f32_16x16x32_bf16 v[100:103], v[170:173], v[194:197], v[100:103]
	v_mfma_f32_16x16x32_bf16 v[96:99], v[178:181], v[194:197], v[96:99]
	v_mfma_f32_16x16x32_bf16 v[84:87], v[170:173], v[202:205], v[84:87]
	v_mfma_f32_16x16x32_bf16 v[80:83], v[178:181], v[202:205], v[80:83]
	v_mfma_f32_16x16x32_bf16 v[68:71], v[170:173], v[210:213], v[68:71]
	v_mfma_f32_16x16x32_bf16 v[64:67], v[178:181], v[210:213], v[64:67]
	v_mfma_f32_16x16x32_bf16 v[116:119], v[174:177], v[190:193], v[116:119]
	v_mfma_f32_16x16x32_bf16 v[112:115], v[182:185], v[190:193], v[112:115]
	v_mfma_f32_16x16x32_bf16 v[100:103], v[174:177], v[198:201], v[100:103]
	v_mfma_f32_16x16x32_bf16 v[96:99], v[182:185], v[198:201], v[96:99]
	v_mfma_f32_16x16x32_bf16 v[84:87], v[174:177], v[206:209], v[84:87]
	v_mfma_f32_16x16x32_bf16 v[80:83], v[182:185], v[206:209], v[80:83]
	v_mfma_f32_16x16x32_bf16 v[68:71], v[174:177], v[214:217], v[68:71]
	v_mfma_f32_16x16x32_bf16 v[64:67], v[182:185], v[214:217], v[64:67]
	s_setprio 0
	s_barrier
	s_add_i32 s52, s42, s9
	v_lshl_add_u64 v[166:167], s[24:25], 0, v[130:131]
	s_mov_b32 m0, s52
	ds_read_b128 v[186:189], v148 offset:16384
	ds_read_b128 v[190:193], v148 offset:17408
	ds_read_b128 v[194:197], v148 offset:18432
	ds_read_b128 v[198:201], v148 offset:19456
	ds_read_b128 v[202:205], v148 offset:20480
	ds_read_b128 v[206:209], v148 offset:21504
	ds_read_b128 v[210:213], v148 offset:22528
	ds_read_b128 v[214:217], v148 offset:23552
	global_load_lds_dwordx4 v[166:167], off
	s_add_i32 m0, s52, 0x2000
	s_add_u32 s52, s24, 0x80000
	v_lshl_add_u64 v[218:219], s[24:25], 0, v[128:129]
	s_addc_u32 s53, s25, 0
	s_add_i32 s54, s43, s9
	global_load_lds_dwordx4 v[218:219], off
	v_lshl_add_u64 v[220:221], s[52:53], 0, v[130:131]
	s_mov_b32 m0, s54
	v_lshl_add_u64 v[222:223], s[26:27], 0, v[128:129]
	global_load_lds_dwordx4 v[220:221], off
	s_add_i32 m0, s54, 0x2000
	v_lshl_add_u64 v[220:221], s[52:53], 0, v[128:129]
	global_load_lds_dwordx4 v[220:221], off
	s_mov_b32 m0, s29
	v_lshl_add_u64 v[220:221], s[26:27], 0, v[130:131]
	global_load_lds_dwordx4 v[220:221], off
	s_mov_b32 m0, s33
	s_nop 0
	global_load_lds_dwordx4 v[222:223], off
	s_waitcnt vmcnt(8)
	s_waitcnt lgkmcnt(0)
	s_barrier
	s_setprio 1
	s_waitcnt lgkmcnt(0)
	v_mfma_f32_16x16x32_bf16 v[60:63], v[150:153], v[186:189], v[60:63]
	v_mfma_f32_16x16x32_bf16 v[56:59], v[158:161], v[186:189], v[56:59]
	v_mfma_f32_16x16x32_bf16 v[44:47], v[150:153], v[194:197], v[44:47]
	v_mfma_f32_16x16x32_bf16 v[40:43], v[158:161], v[194:197], v[40:43]
	v_mfma_f32_16x16x32_bf16 v[28:31], v[150:153], v[202:205], v[28:31]
	v_mfma_f32_16x16x32_bf16 v[24:27], v[158:161], v[202:205], v[24:27]
	v_mfma_f32_16x16x32_bf16 v[12:15], v[150:153], v[210:213], v[12:15]
	v_mfma_f32_16x16x32_bf16 v[8:11], v[158:161], v[210:213], v[8:11]
	v_mfma_f32_16x16x32_bf16 v[60:63], v[154:157], v[190:193], v[60:63]
	v_mfma_f32_16x16x32_bf16 v[56:59], v[162:165], v[190:193], v[56:59]
	v_mfma_f32_16x16x32_bf16 v[44:47], v[154:157], v[198:201], v[44:47]
	v_mfma_f32_16x16x32_bf16 v[40:43], v[162:165], v[198:201], v[40:43]
	v_mfma_f32_16x16x32_bf16 v[28:31], v[154:157], v[206:209], v[28:31]
	v_mfma_f32_16x16x32_bf16 v[24:27], v[162:165], v[206:209], v[24:27]
	v_mfma_f32_16x16x32_bf16 v[12:15], v[154:157], v[214:217], v[12:15]
	v_mfma_f32_16x16x32_bf16 v[8:11], v[162:165], v[214:217], v[8:11]
	s_setprio 0
	s_setprio 1
	v_mfma_f32_16x16x32_bf16 v[52:55], v[170:173], v[186:189], v[52:55]
	v_mfma_f32_16x16x32_bf16 v[48:51], v[178:181], v[186:189], v[48:51]
	v_mfma_f32_16x16x32_bf16 v[36:39], v[170:173], v[194:197], v[36:39]
	v_mfma_f32_16x16x32_bf16 v[32:35], v[178:181], v[194:197], v[32:35]
	v_mfma_f32_16x16x32_bf16 v[20:23], v[170:173], v[202:205], v[20:23]
	v_mfma_f32_16x16x32_bf16 v[16:19], v[178:181], v[202:205], v[16:19]
	v_mfma_f32_16x16x32_bf16 v[4:7], v[170:173], v[210:213], v[4:7]
	v_mfma_f32_16x16x32_bf16 v[0:3], v[178:181], v[210:213], v[0:3]
	v_mfma_f32_16x16x32_bf16 v[52:55], v[174:177], v[190:193], v[52:55]
	v_mfma_f32_16x16x32_bf16 v[48:51], v[182:185], v[190:193], v[48:51]
	v_mfma_f32_16x16x32_bf16 v[36:39], v[174:177], v[198:201], v[36:39]
	v_mfma_f32_16x16x32_bf16 v[32:35], v[182:185], v[198:201], v[32:35]
	v_mfma_f32_16x16x32_bf16 v[20:23], v[174:177], v[206:209], v[20:23]
	v_mfma_f32_16x16x32_bf16 v[16:19], v[182:185], v[206:209], v[16:19]
	v_mfma_f32_16x16x32_bf16 v[4:7], v[174:177], v[214:217], v[4:7]
	v_mfma_f32_16x16x32_bf16 v[0:3], v[182:185], v[214:217], v[0:3]
	s_setprio 0
	s_barrier
	s_add_i32 s52, 0, 0x18000
	v_add_u32_e32 v149, s52, v147
	s_add_i32 s53, 0, 0x1c000
	ds_read_b128 v[150:153], v149
	ds_read_b128 v[154:157], v149 offset:1024
	ds_read_b128 v[158:161], v149 offset:2048
	ds_read_b128 v[162:165], v149 offset:3072
	v_add_u32_e32 v149, s53, v147
	ds_read_b128 v[170:173], v149
	ds_read_b128 v[174:177], v149 offset:1024
	ds_read_b128 v[178:181], v149 offset:2048
	ds_read_b128 v[182:185], v149 offset:3072
	s_add_u32 s26, s26, 0x80000
	s_addc_u32 s27, s27, 0
	s_mov_b32 m0, s36
	v_lshl_add_u64 v[224:225], s[26:27], 0, v[130:131]
	ds_read_b128 v[186:189], v148 offset:32768
	ds_read_b128 v[190:193], v148 offset:33792
	ds_read_b128 v[194:197], v148 offset:34816
	ds_read_b128 v[198:201], v148 offset:35840
	ds_read_b128 v[202:205], v148 offset:36864
	ds_read_b128 v[206:209], v148 offset:37888
	ds_read_b128 v[210:213], v148 offset:38912
	ds_read_b128 v[214:217], v148 offset:39936
	global_load_lds_dwordx4 v[224:225], off
	s_mov_b32 m0, s37
	v_lshl_add_u64 v[224:225], s[26:27], 0, v[128:129]
	global_load_lds_dwordx4 v[224:225], off
	s_waitcnt vmcnt(8)
	s_waitcnt lgkmcnt(0)
	s_barrier
	s_setprio 1
	s_waitcnt lgkmcnt(0)
	v_mfma_f32_16x16x32_bf16 v[124:127], v[150:153], v[186:189], v[124:127]
	v_mfma_f32_16x16x32_bf16 v[120:123], v[158:161], v[186:189], v[120:123]
	v_mfma_f32_16x16x32_bf16 v[108:111], v[150:153], v[194:197], v[108:111]
	v_mfma_f32_16x16x32_bf16 v[104:107], v[158:161], v[194:197], v[104:107]
	v_mfma_f32_16x16x32_bf16 v[92:95], v[150:153], v[202:205], v[92:95]
	v_mfma_f32_16x16x32_bf16 v[88:91], v[158:161], v[202:205], v[88:91]
	v_mfma_f32_16x16x32_bf16 v[76:79], v[150:153], v[210:213], v[76:79]
	v_mfma_f32_16x16x32_bf16 v[72:75], v[158:161], v[210:213], v[72:75]
	v_mfma_f32_16x16x32_bf16 v[124:127], v[154:157], v[190:193], v[124:127]
	v_mfma_f32_16x16x32_bf16 v[120:123], v[162:165], v[190:193], v[120:123]
	v_mfma_f32_16x16x32_bf16 v[108:111], v[154:157], v[198:201], v[108:111]
	v_mfma_f32_16x16x32_bf16 v[104:107], v[162:165], v[198:201], v[104:107]
	v_mfma_f32_16x16x32_bf16 v[92:95], v[154:157], v[206:209], v[92:95]
	v_mfma_f32_16x16x32_bf16 v[88:91], v[162:165], v[206:209], v[88:91]
	v_mfma_f32_16x16x32_bf16 v[76:79], v[154:157], v[214:217], v[76:79]
	v_mfma_f32_16x16x32_bf16 v[72:75], v[162:165], v[214:217], v[72:75]
	s_setprio 0
	s_setprio 1
	v_mfma_f32_16x16x32_bf16 v[116:119], v[170:173], v[186:189], v[116:119]
	v_mfma_f32_16x16x32_bf16 v[112:115], v[178:181], v[186:189], v[112:115]
	v_mfma_f32_16x16x32_bf16 v[100:103], v[170:173], v[194:197], v[100:103]
	v_mfma_f32_16x16x32_bf16 v[96:99], v[178:181], v[194:197], v[96:99]
	v_mfma_f32_16x16x32_bf16 v[84:87], v[170:173], v[202:205], v[84:87]
	v_mfma_f32_16x16x32_bf16 v[80:83], v[178:181], v[202:205], v[80:83]
	v_mfma_f32_16x16x32_bf16 v[68:71], v[170:173], v[210:213], v[68:71]
	v_mfma_f32_16x16x32_bf16 v[64:67], v[178:181], v[210:213], v[64:67]
	v_mfma_f32_16x16x32_bf16 v[116:119], v[174:177], v[190:193], v[116:119]
	v_mfma_f32_16x16x32_bf16 v[112:115], v[182:185], v[190:193], v[112:115]
	v_mfma_f32_16x16x32_bf16 v[100:103], v[174:177], v[198:201], v[100:103]
	v_mfma_f32_16x16x32_bf16 v[96:99], v[182:185], v[198:201], v[96:99]
	v_mfma_f32_16x16x32_bf16 v[84:87], v[174:177], v[206:209], v[84:87]
	v_mfma_f32_16x16x32_bf16 v[80:83], v[182:185], v[206:209], v[80:83]
	v_mfma_f32_16x16x32_bf16 v[68:71], v[174:177], v[214:217], v[68:71]
	v_mfma_f32_16x16x32_bf16 v[64:67], v[182:185], v[214:217], v[64:67]
	s_setprio 0
	s_barrier
	s_add_i32 s26, s52, s9
	v_lshl_add_u64 v[166:167], v[166:167], 0, s[12:13]
	s_mov_b32 m0, s26
	ds_read_b128 v[186:189], v148 offset:49152
	ds_read_b128 v[190:193], v148 offset:50176
	ds_read_b128 v[194:197], v148 offset:51200
	ds_read_b128 v[198:201], v148 offset:52224
	ds_read_b128 v[202:205], v148 offset:53248
	ds_read_b128 v[206:209], v148 offset:54272
	ds_read_b128 v[210:213], v148 offset:55296
	ds_read_b128 v[214:217], v148 offset:56320
	global_load_lds_dwordx4 v[166:167], off
	s_add_i32 m0, s26, 0x2000
	s_add_u32 s24, s24, 0x80080
	v_lshl_add_u64 v[166:167], v[218:219], 0, s[12:13]
	s_addc_u32 s25, s25, 0
	s_add_i32 s26, s53, s9
	global_load_lds_dwordx4 v[166:167], off
	s_mov_b32 m0, s26
	v_lshl_add_u64 v[166:167], s[24:25], 0, v[130:131]
	global_load_lds_dwordx4 v[166:167], off
	s_add_i32 m0, s26, 0x2000
	v_lshl_add_u64 v[166:167], s[24:25], 0, v[128:129]
	global_load_lds_dwordx4 v[166:167], off
	s_mov_b32 m0, s39
	v_lshl_add_u64 v[166:167], v[220:221], 0, s[12:13]
	global_load_lds_dwordx4 v[166:167], off
	s_mov_b32 m0, s40
	v_lshl_add_u64 v[166:167], v[222:223], 0, s[12:13]
	global_load_lds_dwordx4 v[166:167], off
	s_waitcnt vmcnt(8)
	s_waitcnt lgkmcnt(0)
	s_barrier
	s_setprio 1
	s_waitcnt lgkmcnt(0)
	v_mfma_f32_16x16x32_bf16 v[60:63], v[150:153], v[186:189], v[60:63]
	v_mfma_f32_16x16x32_bf16 v[56:59], v[158:161], v[186:189], v[56:59]
	v_mfma_f32_16x16x32_bf16 v[44:47], v[150:153], v[194:197], v[44:47]
	v_mfma_f32_16x16x32_bf16 v[40:43], v[158:161], v[194:197], v[40:43]
	v_mfma_f32_16x16x32_bf16 v[28:31], v[150:153], v[202:205], v[28:31]
	v_mfma_f32_16x16x32_bf16 v[24:27], v[158:161], v[202:205], v[24:27]
	v_mfma_f32_16x16x32_bf16 v[12:15], v[150:153], v[210:213], v[12:15]
	v_mfma_f32_16x16x32_bf16 v[8:11], v[158:161], v[210:213], v[8:11]
	v_mfma_f32_16x16x32_bf16 v[60:63], v[154:157], v[190:193], v[60:63]
	v_mfma_f32_16x16x32_bf16 v[56:59], v[162:165], v[190:193], v[56:59]
	v_mfma_f32_16x16x32_bf16 v[44:47], v[154:157], v[198:201], v[44:47]
	v_mfma_f32_16x16x32_bf16 v[40:43], v[162:165], v[198:201], v[40:43]
	v_mfma_f32_16x16x32_bf16 v[28:31], v[154:157], v[206:209], v[28:31]
	v_mfma_f32_16x16x32_bf16 v[24:27], v[162:165], v[206:209], v[24:27]
	v_mfma_f32_16x16x32_bf16 v[12:15], v[154:157], v[214:217], v[12:15]
	v_mfma_f32_16x16x32_bf16 v[8:11], v[162:165], v[214:217], v[8:11]
	s_setprio 0
	s_setprio 1
	v_mfma_f32_16x16x32_bf16 v[52:55], v[170:173], v[186:189], v[52:55]
	v_mfma_f32_16x16x32_bf16 v[48:51], v[178:181], v[186:189], v[48:51]
	v_mfma_f32_16x16x32_bf16 v[36:39], v[170:173], v[194:197], v[36:39]
	v_mfma_f32_16x16x32_bf16 v[32:35], v[178:181], v[194:197], v[32:35]
	v_mfma_f32_16x16x32_bf16 v[20:23], v[170:173], v[202:205], v[20:23]
	v_mfma_f32_16x16x32_bf16 v[16:19], v[178:181], v[202:205], v[16:19]
	v_mfma_f32_16x16x32_bf16 v[4:7], v[170:173], v[210:213], v[4:7]
	v_mfma_f32_16x16x32_bf16 v[0:3], v[178:181], v[210:213], v[0:3]
	v_mfma_f32_16x16x32_bf16 v[52:55], v[174:177], v[190:193], v[52:55]
	v_mfma_f32_16x16x32_bf16 v[48:51], v[182:185], v[190:193], v[48:51]
	v_mfma_f32_16x16x32_bf16 v[36:39], v[174:177], v[198:201], v[36:39]
	v_mfma_f32_16x16x32_bf16 v[32:35], v[182:185], v[198:201], v[32:35]
	v_mfma_f32_16x16x32_bf16 v[20:23], v[174:177], v[206:209], v[20:23]
	v_mfma_f32_16x16x32_bf16 v[16:19], v[182:185], v[206:209], v[16:19]
	v_mfma_f32_16x16x32_bf16 v[4:7], v[174:177], v[214:217], v[4:7]
	v_mfma_f32_16x16x32_bf16 v[0:3], v[182:185], v[214:217], v[0:3]
	s_setprio 0
	s_barrier
	s_add_i32 s51, s51, 2
	s_add_u32 s22, s22, 0x100
	s_addc_u32 s23, s23, 0
	s_cmp_gt_u32 s51, 29
	s_cbranch_scc0 .LBB0_661
	s_add_u32 s22, s47, 0xffffff00
	s_addc_u32 s23, s48, -1
	s_andn2_b64 vcc, exec, s[4:5]
	s_cbranch_vccnz .LBB0_652
	v_mov_b32_e32 v0, 0
	s_mov_b32 s8, s14
	s_mov_b32 s6, s16
	s_mov_b64 s[10:11], s[20:21]
	s_mov_b32 s41, s46
	v_mov_b32_e32 v1, v0
	v_mov_b32_e32 v2, v0
	v_mov_b32_e32 v3, v0
	v_mov_b32_e32 v4, v0
	v_mov_b32_e32 v5, v0
	v_mov_b32_e32 v6, v0
	v_mov_b32_e32 v7, v0
	v_mov_b32_e32 v16, v0
	v_mov_b32_e32 v17, v0
	v_mov_b32_e32 v18, v0
	v_mov_b32_e32 v19, v0
	v_mov_b32_e32 v20, v0
	v_mov_b32_e32 v21, v0
	v_mov_b32_e32 v22, v0
	v_mov_b32_e32 v23, v0
	v_mov_b32_e32 v32, v0
	v_mov_b32_e32 v33, v0
	v_mov_b32_e32 v34, v0
	v_mov_b32_e32 v35, v0
	v_mov_b32_e32 v36, v0
	v_mov_b32_e32 v37, v0
	v_mov_b32_e32 v38, v0
	v_mov_b32_e32 v39, v0
	v_mov_b32_e32 v48, v0
	v_mov_b32_e32 v49, v0
	v_mov_b32_e32 v50, v0
	v_mov_b32_e32 v51, v0
	v_mov_b32_e32 v52, v0
	v_mov_b32_e32 v53, v0
	v_mov_b32_e32 v54, v0
	v_mov_b32_e32 v55, v0
	v_mov_b32_e32 v8, v0
	v_mov_b32_e32 v9, v0
	v_mov_b32_e32 v10, v0
	v_mov_b32_e32 v11, v0
	v_mov_b32_e32 v12, v0
	v_mov_b32_e32 v13, v0
	v_mov_b32_e32 v14, v0
	v_mov_b32_e32 v15, v0
	v_mov_b32_e32 v24, v0
	v_mov_b32_e32 v25, v0
	v_mov_b32_e32 v26, v0
	v_mov_b32_e32 v27, v0
	v_mov_b32_e32 v28, v0
	v_mov_b32_e32 v29, v0
	v_mov_b32_e32 v30, v0
	v_mov_b32_e32 v31, v0
	v_mov_b32_e32 v40, v0
	v_mov_b32_e32 v41, v0
	v_mov_b32_e32 v42, v0
	v_mov_b32_e32 v43, v0
	v_mov_b32_e32 v44, v0
	v_mov_b32_e32 v45, v0
	v_mov_b32_e32 v46, v0
	v_mov_b32_e32 v47, v0
	v_mov_b32_e32 v56, v0
	v_mov_b32_e32 v57, v0
	v_mov_b32_e32 v58, v0
	v_mov_b32_e32 v59, v0
	v_mov_b32_e32 v60, v0
	v_mov_b32_e32 v61, v0
	v_mov_b32_e32 v62, v0
	v_mov_b32_e32 v63, v0
	v_mov_b32_e32 v64, v0
	v_mov_b32_e32 v65, v0
	v_mov_b32_e32 v66, v0
	v_mov_b32_e32 v67, v0
	v_mov_b32_e32 v68, v0
	v_mov_b32_e32 v69, v0
	v_mov_b32_e32 v70, v0
	v_mov_b32_e32 v71, v0
	v_mov_b32_e32 v80, v0
	v_mov_b32_e32 v81, v0
	v_mov_b32_e32 v82, v0
	v_mov_b32_e32 v83, v0
	v_mov_b32_e32 v84, v0
	v_mov_b32_e32 v85, v0
	v_mov_b32_e32 v86, v0
	v_mov_b32_e32 v87, v0
	v_mov_b32_e32 v96, v0
	v_mov_b32_e32 v97, v0
	v_mov_b32_e32 v98, v0
	v_mov_b32_e32 v99, v0
	v_mov_b32_e32 v100, v0
	v_mov_b32_e32 v101, v0
	v_mov_b32_e32 v102, v0
	v_mov_b32_e32 v103, v0
	v_mov_b32_e32 v112, v0
	v_mov_b32_e32 v113, v0
	v_mov_b32_e32 v114, v0
	v_mov_b32_e32 v115, v0
	v_mov_b32_e32 v116, v0
	v_mov_b32_e32 v117, v0
	v_mov_b32_e32 v118, v0
	v_mov_b32_e32 v119, v0
	v_mov_b32_e32 v72, v0
	v_mov_b32_e32 v73, v0
	v_mov_b32_e32 v74, v0
	v_mov_b32_e32 v75, v0
	v_mov_b32_e32 v76, v0
	v_mov_b32_e32 v77, v0
	v_mov_b32_e32 v78, v0
	v_mov_b32_e32 v79, v0
	v_mov_b32_e32 v88, v0
	v_mov_b32_e32 v89, v0
	v_mov_b32_e32 v90, v0
	v_mov_b32_e32 v91, v0
	v_mov_b32_e32 v92, v0
	v_mov_b32_e32 v93, v0
	v_mov_b32_e32 v94, v0
	v_mov_b32_e32 v95, v0
	v_mov_b32_e32 v104, v0
	v_mov_b32_e32 v105, v0
	v_mov_b32_e32 v106, v0
	v_mov_b32_e32 v107, v0
	v_mov_b32_e32 v108, v0
	v_mov_b32_e32 v109, v0
	v_mov_b32_e32 v110, v0
	v_mov_b32_e32 v111, v0
	v_mov_b32_e32 v120, v0
	v_mov_b32_e32 v121, v0
	v_mov_b32_e32 v122, v0
	v_mov_b32_e32 v123, v0
	v_mov_b32_e32 v124, v0
	v_mov_b32_e32 v125, v0
	v_mov_b32_e32 v126, v0
	v_mov_b32_e32 v127, v0
	s_andn2_b64 vcc, exec, s[0:1]
	s_cbranch_vccnz .LBB0_653
